# ssd_scan chunk loop: 16 chunk loads per rep issued up front, recurrence under counted vmcnt
# speedup vs baseline: 1.0029x; 1.0029x over previous
.LBB0_708:
	s_and_b64 s[18:19], s[20:21], exec
	s_cselect_b32 s2, s2, 0
	v_add_u32_e32 v0, s2, v5
	v_ashrrev_i32_e32 v14, 14, v0
	v_ashrrev_i32_e32 v15, 31, v14
	v_lshlrev_b64 v[0:1], 20, v[14:15]
	v_or_b32_e32 v0, v12, v0
	v_mov_b64_e32 v[2:3], 0x4f690200
	v_lshl_add_u64 v[22:23], v[0:1], 1, v[2:3]
	v_mov_b64_e32 v[2:3], 0x4d690200
	v_lshlrev_b64 v[16:17], 9, v[14:15]
	v_lshlrev_b64 v[18:19], 22, v[14:15]
	v_lshlrev_b64 v[20:21], 21, v[14:15]
	v_lshl_add_u64 v[24:25], v[0:1], 2, v[2:3]
	v_mov_b32_e32 v0, 0
	v_or_b32_e32 v16, v4, v16
	v_or_b32_e32 v18, v8, v18
	v_or_b32_e32 v20, v10, v20
	s_mov_b32 s18, 16
	v_mov_b32_e32 v1, v0
	v_mov_b32_e32 v2, v0
	v_mov_b32_e32 v3, v0
	s_waitcnt vmcnt(8)
	v_lshl_add_u64 v[26:27], s[14:15], 0, v[16:17]
	s_mov_b32 s2, 0x4ce8f000
	v_add_co_u32_e32 v26, vcc, s2, v26
	s_mov_b64 s[18:19], 0x40000
	v_lshl_add_u64 v[28:29], s[14:15], 0, v[24:25]
	v_lshl_add_u64 v[30:31], s[14:15], 0, v[22:23]
	v_addc_co_u32_e32 v27, vcc, 0, v27, vcc
	global_load_dwordx4 v[186:189], v[28:29], off
	global_load_dword v158, v[26:27], off offset:512
	v_lshl_add_u64 v[28:29], v[28:29], 0, s[18:19]
	global_load_dwordx4 v[190:193], v[28:29], off
	global_load_dword v159, v[26:27], off offset:544
	v_lshl_add_u64 v[28:29], v[28:29], 0, s[18:19]
	global_load_dwordx4 v[194:197], v[28:29], off
	global_load_dword v160, v[26:27], off offset:576
	v_lshl_add_u64 v[28:29], v[28:29], 0, s[18:19]
	global_load_dwordx4 v[198:201], v[28:29], off
	global_load_dword v161, v[26:27], off offset:608
	v_lshl_add_u64 v[28:29], v[28:29], 0, s[18:19]
	global_load_dwordx4 v[202:205], v[28:29], off
	global_load_dword v162, v[26:27], off offset:640
	v_lshl_add_u64 v[28:29], v[28:29], 0, s[18:19]
	global_load_dwordx4 v[206:209], v[28:29], off
	global_load_dword v163, v[26:27], off offset:672
	v_lshl_add_u64 v[28:29], v[28:29], 0, s[18:19]
	global_load_dwordx4 v[210:213], v[28:29], off
	global_load_dword v164, v[26:27], off offset:704
	v_lshl_add_u64 v[28:29], v[28:29], 0, s[18:19]
	global_load_dwordx4 v[214:217], v[28:29], off
	global_load_dword v165, v[26:27], off offset:736
	v_lshl_add_u64 v[28:29], v[28:29], 0, s[18:19]
	global_load_dwordx4 v[218:221], v[28:29], off
	global_load_dword v166, v[26:27], off offset:768
	v_lshl_add_u64 v[28:29], v[28:29], 0, s[18:19]
	global_load_dwordx4 v[222:225], v[28:29], off
	global_load_dword v167, v[26:27], off offset:800
	v_lshl_add_u64 v[28:29], v[28:29], 0, s[18:19]
	global_load_dwordx4 v[226:229], v[28:29], off
	global_load_dword v168, v[26:27], off offset:832
	v_lshl_add_u64 v[28:29], v[28:29], 0, s[18:19]
	global_load_dwordx4 v[230:233], v[28:29], off
	global_load_dword v169, v[26:27], off offset:864
	v_lshl_add_u64 v[28:29], v[28:29], 0, s[18:19]
	global_load_dwordx4 v[236:239], v[28:29], off
	global_load_dword v170, v[26:27], off offset:896
	v_lshl_add_u64 v[28:29], v[28:29], 0, s[18:19]
	global_load_dwordx4 v[240:243], v[28:29], off
	global_load_dword v171, v[26:27], off offset:928
	v_lshl_add_u64 v[28:29], v[28:29], 0, s[18:19]
	global_load_dwordx4 v[244:247], v[28:29], off
	global_load_dword v172, v[26:27], off offset:960
	v_lshl_add_u64 v[28:29], v[28:29], 0, s[18:19]
	global_load_dwordx4 v[248:251], v[28:29], off
	global_load_dword v173, v[26:27], off offset:992
	s_mov_b64 vcc, 0x20000
	v_cvt_pk_bf16_f32 v32, v0, v1
	v_cvt_pk_bf16_f32 v33, v2, v3
	global_store_dwordx2 v[30:31], v[32:33], off
	v_lshl_add_u64 v[30:31], v[30:31], 0, vcc
	s_waitcnt vmcnt(31)
	v_pk_fma_f32 v[2:3], v[2:3], v[158:159], v[188:189] op_sel_hi:[1,0,1]
	v_pk_fma_f32 v[0:1], v[0:1], v[158:159], v[186:187] op_sel_hi:[1,0,1]
	v_cvt_pk_bf16_f32 v34, v0, v1
	v_cvt_pk_bf16_f32 v35, v2, v3
	global_store_dwordx2 v[30:31], v[34:35], off
	v_lshl_add_u64 v[30:31], v[30:31], 0, vcc
	s_waitcnt vmcnt(30)
	v_pk_fma_f32 v[2:3], v[2:3], v[158:159], v[192:193] op_sel:[0,1,0]
	v_pk_fma_f32 v[0:1], v[0:1], v[158:159], v[190:191] op_sel:[0,1,0]
	v_cvt_pk_bf16_f32 v32, v0, v1
	v_cvt_pk_bf16_f32 v33, v2, v3
	global_store_dwordx2 v[30:31], v[32:33], off
	v_lshl_add_u64 v[30:31], v[30:31], 0, vcc
	s_waitcnt vmcnt(29)
	v_pk_fma_f32 v[2:3], v[2:3], v[160:161], v[196:197] op_sel_hi:[1,0,1]
	v_pk_fma_f32 v[0:1], v[0:1], v[160:161], v[194:195] op_sel_hi:[1,0,1]
	v_cvt_pk_bf16_f32 v34, v0, v1
	v_cvt_pk_bf16_f32 v35, v2, v3
	global_store_dwordx2 v[30:31], v[34:35], off
	v_lshl_add_u64 v[30:31], v[30:31], 0, vcc
	s_waitcnt vmcnt(28)
	v_pk_fma_f32 v[2:3], v[2:3], v[160:161], v[200:201] op_sel:[0,1,0]
	v_pk_fma_f32 v[0:1], v[0:1], v[160:161], v[198:199] op_sel:[0,1,0]
	v_cvt_pk_bf16_f32 v32, v0, v1
	v_cvt_pk_bf16_f32 v33, v2, v3
	global_store_dwordx2 v[30:31], v[32:33], off
	v_lshl_add_u64 v[30:31], v[30:31], 0, vcc
	s_waitcnt vmcnt(27)
	v_pk_fma_f32 v[2:3], v[2:3], v[162:163], v[204:205] op_sel_hi:[1,0,1]
	v_pk_fma_f32 v[0:1], v[0:1], v[162:163], v[202:203] op_sel_hi:[1,0,1]
	v_cvt_pk_bf16_f32 v34, v0, v1
	v_cvt_pk_bf16_f32 v35, v2, v3
	global_store_dwordx2 v[30:31], v[34:35], off
	v_lshl_add_u64 v[30:31], v[30:31], 0, vcc
	s_waitcnt vmcnt(26)
	v_pk_fma_f32 v[2:3], v[2:3], v[162:163], v[208:209] op_sel:[0,1,0]
	v_pk_fma_f32 v[0:1], v[0:1], v[162:163], v[206:207] op_sel:[0,1,0]
	v_cvt_pk_bf16_f32 v32, v0, v1
	v_cvt_pk_bf16_f32 v33, v2, v3
	global_store_dwordx2 v[30:31], v[32:33], off
	v_lshl_add_u64 v[30:31], v[30:31], 0, vcc
	s_waitcnt vmcnt(25)
	v_pk_fma_f32 v[2:3], v[2:3], v[164:165], v[212:213] op_sel_hi:[1,0,1]
	v_pk_fma_f32 v[0:1], v[0:1], v[164:165], v[210:211] op_sel_hi:[1,0,1]
	v_cvt_pk_bf16_f32 v34, v0, v1
	v_cvt_pk_bf16_f32 v35, v2, v3
	global_store_dwordx2 v[30:31], v[34:35], off
	v_lshl_add_u64 v[30:31], v[30:31], 0, vcc
	s_waitcnt vmcnt(24)
	v_pk_fma_f32 v[2:3], v[2:3], v[164:165], v[216:217] op_sel:[0,1,0]
	v_pk_fma_f32 v[0:1], v[0:1], v[164:165], v[214:215] op_sel:[0,1,0]
	v_cvt_pk_bf16_f32 v32, v0, v1
	v_cvt_pk_bf16_f32 v33, v2, v3
	global_store_dwordx2 v[30:31], v[32:33], off
	v_lshl_add_u64 v[30:31], v[30:31], 0, vcc
	s_waitcnt vmcnt(23)
	v_pk_fma_f32 v[2:3], v[2:3], v[166:167], v[220:221] op_sel_hi:[1,0,1]
	v_pk_fma_f32 v[0:1], v[0:1], v[166:167], v[218:219] op_sel_hi:[1,0,1]
	v_cvt_pk_bf16_f32 v34, v0, v1
	v_cvt_pk_bf16_f32 v35, v2, v3
	global_store_dwordx2 v[30:31], v[34:35], off
	v_lshl_add_u64 v[30:31], v[30:31], 0, vcc
	s_waitcnt vmcnt(22)
	v_pk_fma_f32 v[2:3], v[2:3], v[166:167], v[224:225] op_sel:[0,1,0]
	v_pk_fma_f32 v[0:1], v[0:1], v[166:167], v[222:223] op_sel:[0,1,0]
	v_cvt_pk_bf16_f32 v32, v0, v1
	v_cvt_pk_bf16_f32 v33, v2, v3
	global_store_dwordx2 v[30:31], v[32:33], off
	v_lshl_add_u64 v[30:31], v[30:31], 0, vcc
	s_waitcnt vmcnt(21)
	v_pk_fma_f32 v[2:3], v[2:3], v[168:169], v[228:229] op_sel_hi:[1,0,1]
	v_pk_fma_f32 v[0:1], v[0:1], v[168:169], v[226:227] op_sel_hi:[1,0,1]
	v_cvt_pk_bf16_f32 v34, v0, v1
	v_cvt_pk_bf16_f32 v35, v2, v3
	global_store_dwordx2 v[30:31], v[34:35], off
	v_lshl_add_u64 v[30:31], v[30:31], 0, vcc
	s_waitcnt vmcnt(20)
	v_pk_fma_f32 v[2:3], v[2:3], v[168:169], v[232:233] op_sel:[0,1,0]
	v_pk_fma_f32 v[0:1], v[0:1], v[168:169], v[230:231] op_sel:[0,1,0]
	v_cvt_pk_bf16_f32 v32, v0, v1
	v_cvt_pk_bf16_f32 v33, v2, v3
	global_store_dwordx2 v[30:31], v[32:33], off
	v_lshl_add_u64 v[30:31], v[30:31], 0, vcc
	s_waitcnt vmcnt(19)
	v_pk_fma_f32 v[2:3], v[2:3], v[170:171], v[238:239] op_sel_hi:[1,0,1]
	v_pk_fma_f32 v[0:1], v[0:1], v[170:171], v[236:237] op_sel_hi:[1,0,1]
	v_cvt_pk_bf16_f32 v34, v0, v1
	v_cvt_pk_bf16_f32 v35, v2, v3
	global_store_dwordx2 v[30:31], v[34:35], off
	v_lshl_add_u64 v[30:31], v[30:31], 0, vcc
	s_waitcnt vmcnt(18)
	v_pk_fma_f32 v[2:3], v[2:3], v[170:171], v[242:243] op_sel:[0,1,0]
	v_pk_fma_f32 v[0:1], v[0:1], v[170:171], v[240:241] op_sel:[0,1,0]
	v_cvt_pk_bf16_f32 v32, v0, v1
	v_cvt_pk_bf16_f32 v33, v2, v3
	global_store_dwordx2 v[30:31], v[32:33], off
	v_lshl_add_u64 v[30:31], v[30:31], 0, vcc
	s_waitcnt vmcnt(17)
	v_pk_fma_f32 v[2:3], v[2:3], v[172:173], v[246:247] op_sel_hi:[1,0,1]
	v_pk_fma_f32 v[0:1], v[0:1], v[172:173], v[244:245] op_sel_hi:[1,0,1]
	v_cvt_pk_bf16_f32 v34, v0, v1
	v_cvt_pk_bf16_f32 v35, v2, v3
	global_store_dwordx2 v[30:31], v[34:35], off
	s_waitcnt vmcnt(16)
	v_pk_fma_f32 v[2:3], v[2:3], v[172:173], v[250:251] op_sel:[0,1,0]
	v_pk_fma_f32 v[0:1], v[0:1], v[172:173], v[248:249] op_sel:[0,1,0]
	v_lshlrev_b64 v[14:15], 18, v[14:15]
	s_and_b64 s[16:17], s[20:21], s[16:17]
	v_lshl_add_u64 v[14:15], v[6:7], 0, v[14:15]
	s_mov_b32 s2, 0
	s_andn2_b64 vcc, exec, s[16:17]
	s_mov_b64 s[16:17], 0
	global_store_dwordx4 v[14:15], v[0:3], off
	s_cbranch_vccz .LBB0_708
	s_branch .LBB0_705
